# attention K tile: 4-bit xor swizzle (row&15) so the 16-lane ds_read_b128 groups are bank-conflict free; +128 reads get their own base registers
# speedup vs baseline: 1.0046x; 1.0046x over previous
.LBB0_370:
	s_cmpk_gt_i32 s2, 0x1ff
	s_waitcnt vmcnt(0) lgkmcnt(0)
	s_barrier
	s_cbranch_scc1 .LBB0_432
	s_add_u32 s17, s78, 0x6800000
	s_addc_u32 s58, s79, 0
	s_add_u32 s59, s78, 0xa800000
	s_addc_u32 s60, s79, 0
	s_add_u32 s61, s78, 0xe800000
	s_addc_u32 s62, s79, 0
	s_add_u32 s63, s78, 0x12800000
	s_addc_u32 s64, s79, 0
	s_add_u32 s65, s78, 0x200000
	s_addc_u32 s66, s79, 0
	s_ashr_i32 s0, s2, 3
	s_lshr_b32 s1, s0, 29
	s_add_i32 s1, s0, s1
	s_and_b32 s1, s1, -8
	s_sub_i32 s0, s0, s1
	s_ashr_i32 s4, s0, 31
	s_lshr_b32 s4, s4, 29
	s_add_i32 s4, s0, s4
	s_ashr_i32 s5, s4, 3
	s_and_b32 s4, s4, -8
	s_sub_i32 s0, s0, s4
	s_sub_i32 s67, 15, s0
	s_cmp_lt_i32 s0, 0
	s_cselect_b32 s10, s67, s0
	s_lshl_b32 s8, s10, 8
	s_bfe_u32 s0, s10, 0x60011
	s_or_b32 s0, s0, s8
	s_addk_i32 s0, 0xff
	s_sext_i32_i16 s0, s0
	s_and_b32 s6, s0, 0xffffffc0
	s_and_b32 s0, s2, 7
	s_or_b32 s0, s1, s0
	s_add_i32 s12, s5, s0
	s_and_b32 s7, s12, 7
	s_lshl_b32 s0, s7, 17
	s_add_u32 s11, s28, s0
	s_addc_u32 s13, s29, 0
	s_lshl_b32 s0, s12, 9
	s_and_b32 s0, s0, 0xfffff000
	s_ashr_i32 s1, s0, 31
	s_lshl_b64 s[4:5], s[0:1], 2
	s_mov_b32 s9, 0
	s_add_u32 s1, s11, s4
	s_addc_u32 s11, s13, s5
	s_lshl_b64 s[4:5], s[8:9], 2
	s_add_u32 s18, s1, s4
	s_addc_u32 s19, s11, s5
	s_ashr_i32 s13, s12, 31
	s_lshl_b64 s[4:5], s[12:13], 14
	s_add_u32 s52, s65, s4
	s_addc_u32 s53, s66, s5
	s_add_i32 s0, s0, s8
	s_ashr_i32 s1, s0, 31
	s_lshl_b64 s[0:1], s[0:1], 11
	s_add_u32 s0, s63, s0
	s_addc_u32 s1, s64, s1
	s_lshl_b32 s4, s7, 8
	s_add_u32 s50, s0, s4
	s_addc_u32 s51, s1, 0
	s_lshl_b64 s[0:1], s[12:13], 20
	s_add_u32 s54, s61, s0
	s_addc_u32 s55, s62, s1
	s_add_u32 s56, s59, s0
	s_mov_b32 s11, s9
	s_addc_u32 s57, s60, s1
	s_lshl_b64 s[4:5], s[10:11], 16
	s_add_u32 s4, s17, s4
	s_addc_u32 s5, s58, s5
	v_mov_b32_e32 v10, v254
	s_add_u32 s14, s4, s0
	s_addc_u32 s15, s5, s1
	v_readfirstlane_b32 s0, v10
	s_ashr_i32 s0, s0, 1
	s_movk_i32 s1, 0xffe0
	v_mov_b32_e32 v0, s0
	v_bfi_b32 v0, s1, v0, v10
	v_ashrrev_i32_e32 v1, 31, v0
	v_lshlrev_b64 v[0:1], 8, v[0:1]
	v_lshl_add_u64 v[2:3], s[14:15], 0, v[0:1]
	v_lshrrev_b32_e32 v0, 1, v10
	v_and_b32_e32 v0, 16, v0
	v_mov_b32_e32 v1, 0
	v_lshl_add_u64 v[2:3], v[2:3], 0, v[0:1]
	v_ashrrev_i32_e32 v11, 4, v10
	global_load_dwordx4 v[158:161], v[2:3], off
	global_load_dwordx4 v[154:157], v[2:3], off offset:32
	global_load_dwordx4 v[150:153], v[2:3], off offset:64
	global_load_dwordx4 v[146:149], v[2:3], off offset:96
	global_load_dwordx4 v[142:145], v[2:3], off offset:128
	global_load_dwordx4 v[138:141], v[2:3], off offset:160
	global_load_dwordx4 v[134:137], v[2:3], off offset:192
	global_load_dwordx4 v[130:133], v[2:3], off offset:224
	v_add_u32_e32 v2, s6, v11
	v_ashrrev_i32_e32 v3, 31, v2
	v_lshlrev_b32_e32 v12, 4, v10
	v_lshlrev_b64 v[2:3], 8, v[2:3]
	s_mov_b64 s[0:1], 0x2000
	v_and_b32_e32 v0, 0xf0, v12
	v_lshl_add_u64 v[4:5], s[54:55], 0, v[2:3]
	v_lshl_add_u64 v[6:7], v[2:3], 0, s[0:1]
	v_lshl_add_u64 v[2:3], s[56:57], 0, v[2:3]
	v_lshl_add_u64 v[2:3], v[2:3], 0, v[0:1]
	v_lshl_add_u64 v[8:9], s[56:57], 0, v[6:7]
	v_lshl_add_u64 v[8:9], v[8:9], 0, v[0:1]
	global_load_dwordx4 v[106:109], v[2:3], off
	global_load_dwordx4 v[110:113], v[8:9], off
	v_lshl_add_u64 v[2:3], v[4:5], 0, v[0:1]
	v_lshl_add_u64 v[4:5], s[54:55], 0, v[6:7]
	v_lshl_add_u64 v[4:5], v[4:5], 0, v[0:1]
	global_load_dwordx4 v[98:101], v[2:3], off
	global_load_dwordx4 v[102:105], v[4:5], off
	v_mbcnt_lo_u32_b32 v0, -1, 0
	s_movk_i32 s0, 0xf0
	v_mbcnt_hi_u32_b32 v204, -1, v0
	v_and_b32_e32 v0, 0xf0, v10
	s_waitcnt vmcnt(0)
	v_lshlrev_b32_e32 v2, 8, v11
	v_bitop3_b32 v0, v12, v0, s0 bitop3:0x6c
	s_movk_i32 s11, 0x1000
	s_movk_i32 s68, 0xefff
	s_mov_b32 s69, 0x41000000
	s_mov_b32 s16, 0x3e0293ee
	s_movk_i32 s72, 0xf800
	v_mov_b32_e32 v202, 0xff800000
	v_mov_b32_e32 v192, 0xf149f2ca
	v_add3_u32 v0, 0, v2, v0
	s_mov_b32 s73, s2
	s_waitcnt vmcnt(3)
	ds_write_b128 v0, v[106:109] offset:32768
	s_waitcnt vmcnt(2)
	ds_write_b128 v0, v[110:113] offset:40960
	s_waitcnt lgkmcnt(0)
	s_barrier
	s_branch .LBB0_373

.LBB0_383:
	s_ashr_i32 s13, s33, 6
	v_and_b32_e32 v212, 31, v49
	s_lshl_b32 s48, s13, 5
	v_lshlrev_b32_e32 v2, 2, v66
	v_sub_u32_e32 v3, v212, v2
	s_add_i32 s1, s48, s8
	v_add_u32_e32 v210, s1, v3
	v_lshlrev_b32_e32 v4, 4, v49
	v_lshlrev_b32_e32 v200, 4, v66
	v_and_b32_e32 v78, 0xf0, v4
	v_lshlrev_b32_e32 v3, 8, v212
	v_xad_u32 v4, v200, v78, 0
	v_add_u32_e32 v214, v4, v3
	v_or_b32_e32 v196, 0x80, v200
	v_xad_u32 v196, v196, v78, 0
	v_add_u32_e32 v196, v196, v3
	v_or_b32_e32 v197, 0xa0, v200
	v_xad_u32 v197, v197, v78, 0
	v_add_u32_e32 v197, v197, v3
	v_or_b32_e32 v198, 0xc0, v200
	v_xad_u32 v198, v198, v78, 0
	v_add_u32_e32 v198, v198, v3
	v_or_b32_e32 v199, 0xe0, v200
	v_xad_u32 v199, v199, v78, 0
	v_add_u32_e32 v199, v199, v3
	ds_read_b128 v[4:7], v214 offset:32768
	ds_read_b128 v[8:11], v196 offset:32768
	v_or_b32_e32 v12, 32, v200
	s_waitcnt vmcnt(2) lgkmcnt(1)
	v_mfma_f32_32x32x16_bf16 v[32:47], v[4:7], v[158:161], v[32:47]
	ds_read_b128 v[4:7], v214 offset:40960
	v_xad_u32 v12, v12, v78, 0
	v_add_u32_e32 v215, v12, v3
	ds_read_b128 v[12:15], v196 offset:40960
	v_or_b32_e32 v70, 64, v200
	v_xad_u32 v70, v70, v78, 0
	v_add_u32_e32 v216, v70, v3
	s_waitcnt vmcnt(0) lgkmcnt(1)
	v_mfma_f32_32x32x16_bf16 v[16:31], v[4:7], v[158:161], v[16:31]
	ds_read_b128 v[4:7], v215 offset:32768
	ds_read_b128 v[66:69], v197 offset:32768
	ds_read_b128 v[70:73], v197 offset:40960
	v_or_b32_e32 v79, 0x60, v200
	v_xad_u32 v78, v79, v78, 0
	v_add_u32_e32 v217, v78, v3
	s_or_b32 s6, s49, 63
	s_cmp_le_i32 s6, s1
	s_waitcnt lgkmcnt(2)
	v_mfma_f32_32x32x16_bf16 v[32:47], v[4:7], v[154:157], v[32:47]
	ds_read_b128 v[4:7], v215 offset:40960
	s_cselect_b64 s[6:7], -1, 0
	s_add_i32 s8, s1, 0xfffff01f
	s_cmp_gt_i32 s49, s8
	s_cselect_b64 s[80:81], -1, 0
	s_and_b64 s[6:7], s[6:7], s[80:81]
	s_and_b64 vcc, exec, s[6:7]
	s_waitcnt lgkmcnt(0)
	v_mfma_f32_32x32x16_bf16 v[16:31], v[4:7], v[154:157], v[16:31]
	ds_read_b128 v[4:7], v216 offset:32768
	ds_read_b128 v[74:77], v198 offset:32768
	ds_read_b128 v[78:81], v198 offset:40960
	s_waitcnt lgkmcnt(2)
	v_mfma_f32_32x32x16_bf16 v[32:47], v[4:7], v[150:153], v[32:47]
	ds_read_b128 v[4:7], v216 offset:40960
	s_waitcnt lgkmcnt(0)
	v_mfma_f32_32x32x16_bf16 v[16:31], v[4:7], v[150:153], v[16:31]
	ds_read_b128 v[4:7], v217 offset:32768
	ds_read_b128 v[114:117], v199 offset:32768
	s_waitcnt lgkmcnt(1)
	v_mfma_f32_32x32x16_bf16 v[32:47], v[4:7], v[146:149], v[32:47]
	ds_read_b128 v[4:7], v217 offset:40960
	ds_read_b128 v[118:121], v199 offset:40960
	s_waitcnt lgkmcnt(1)
	v_mfma_f32_32x32x16_bf16 v[16:31], v[4:7], v[146:149], v[16:31]
	v_mfma_f32_32x32x16_bf16 v[32:47], v[8:11], v[142:145], v[32:47]
	v_mfma_f32_32x32x16_bf16 v[16:31], v[12:15], v[142:145], v[16:31]
	v_mfma_f32_32x32x16_bf16 v[32:47], v[66:69], v[138:141], v[32:47]
	v_mfma_f32_32x32x16_bf16 v[16:31], v[70:73], v[138:141], v[16:31]
	v_mfma_f32_32x32x16_bf16 v[32:47], v[74:77], v[134:137], v[32:47]
	v_mfma_f32_32x32x16_bf16 v[16:31], v[78:81], v[134:137], v[16:31]
	v_mfma_f32_32x32x16_bf16 v[32:47], v[114:117], v[130:133], v[32:47]
	s_waitcnt lgkmcnt(0)
	v_mfma_f32_32x32x16_bf16 v[16:31], v[118:121], v[130:133], v[16:31]
	s_cbranch_vccnz .LBB0_385
	v_subrev_u32_e32 v3, s49, v210
	v_cmp_gt_u32_e32 vcc, s11, v3
	v_add_u32_e32 v4, 0xffffefe0, v3
	s_nop 5
	v_cndmask_b32_e32 v32, v202, v32, vcc
	v_cmp_lt_u32_e32 vcc, s68, v4
	v_add_u32_e32 v4, 0xffffefff, v3
	s_nop 0
	v_cndmask_b32_e32 v16, v202, v16, vcc
	v_cmp_lt_u32_e32 vcc, s68, v4
	v_add_u32_e32 v4, 0xffffefdf, v3
	s_nop 0
	v_cndmask_b32_e32 v33, v202, v33, vcc
	v_cmp_lt_u32_e32 vcc, s68, v4
	v_add_u32_e32 v4, 0xffffeffe, v3
	s_nop 0
	v_cndmask_b32_e32 v17, v202, v17, vcc
	v_cmp_lt_u32_e32 vcc, s68, v4
	v_add_u32_e32 v4, 0xffffefde, v3
	s_nop 0
	v_cndmask_b32_e32 v34, v202, v34, vcc
	v_cmp_lt_u32_e32 vcc, s68, v4
	v_add_u32_e32 v4, 0xffffeffd, v3
	s_nop 0
	v_cndmask_b32_e32 v18, v202, v18, vcc
	v_cmp_lt_u32_e32 vcc, s68, v4
	v_add_u32_e32 v4, 0xffffefdd, v3
	s_nop 0
	v_cndmask_b32_e32 v35, v202, v35, vcc
	v_cmp_lt_u32_e32 vcc, s68, v4
	v_add_u32_e32 v4, 0xffffeff8, v3
	s_nop 0
	v_cndmask_b32_e32 v19, v202, v19, vcc
	v_cmp_lt_u32_e32 vcc, s68, v4
	v_add_u32_e32 v4, 0xffffefd8, v3
	s_nop 0
	v_cndmask_b32_e32 v36, v202, v36, vcc
	v_cmp_lt_u32_e32 vcc, s68, v4
	v_add_u32_e32 v4, 0xffffeff7, v3
	s_nop 0
	v_cndmask_b32_e32 v20, v202, v20, vcc
	v_cmp_lt_u32_e32 vcc, s68, v4
	v_add_u32_e32 v4, 0xffffefd7, v3
	s_nop 0
	v_cndmask_b32_e32 v37, v202, v37, vcc
	v_cmp_lt_u32_e32 vcc, s68, v4
	v_add_u32_e32 v4, 0xffffeff6, v3
	s_nop 0
	v_cndmask_b32_e32 v21, v202, v21, vcc
	v_cmp_lt_u32_e32 vcc, s68, v4
	v_add_u32_e32 v4, 0xffffefd6, v3
	s_nop 0
	v_cndmask_b32_e32 v38, v202, v38, vcc
	v_cmp_lt_u32_e32 vcc, s68, v4
	v_add_u32_e32 v4, 0xffffeff5, v3
	s_nop 0
	v_cndmask_b32_e32 v22, v202, v22, vcc
	v_cmp_lt_u32_e32 vcc, s68, v4
	v_add_u32_e32 v4, 0xffffefd5, v3
	s_nop 0
	v_cndmask_b32_e32 v39, v202, v39, vcc
	v_cmp_lt_u32_e32 vcc, s68, v4
	v_add_u32_e32 v4, 0xffffeff0, v3
	s_nop 0
	v_cndmask_b32_e32 v23, v202, v23, vcc
	v_cmp_lt_u32_e32 vcc, s68, v4
	v_add_u32_e32 v4, 0xffffefd0, v3
	s_nop 0
	v_cndmask_b32_e32 v40, v202, v40, vcc
	v_cmp_lt_u32_e32 vcc, s68, v4
	v_add_u32_e32 v4, 0xffffefef, v3
	s_nop 0
	v_cndmask_b32_e32 v24, v202, v24, vcc
	v_cmp_lt_u32_e32 vcc, s68, v4
	v_add_u32_e32 v4, 0xffffefcf, v3
	s_nop 0
	v_cndmask_b32_e32 v41, v202, v41, vcc
	v_cmp_lt_u32_e32 vcc, s68, v4
	v_add_u32_e32 v4, 0xffffefee, v3
	s_nop 0
	v_cndmask_b32_e32 v25, v202, v25, vcc
	v_cmp_lt_u32_e32 vcc, s68, v4
	v_add_u32_e32 v4, 0xffffefce, v3
	s_nop 0
	v_cndmask_b32_e32 v42, v202, v42, vcc
	v_cmp_lt_u32_e32 vcc, s68, v4
	v_add_u32_e32 v4, 0xffffefed, v3
	s_nop 0
	v_cndmask_b32_e32 v26, v202, v26, vcc
	v_cmp_lt_u32_e32 vcc, s68, v4
	v_add_u32_e32 v4, 0xffffefcd, v3
	s_nop 0
	v_cndmask_b32_e32 v43, v202, v43, vcc
	v_cmp_lt_u32_e32 vcc, s68, v4
	v_add_u32_e32 v4, 0xffffefe8, v3
	s_nop 0
	v_cndmask_b32_e32 v27, v202, v27, vcc
	v_cmp_lt_u32_e32 vcc, s68, v4
	v_add_u32_e32 v4, 0xffffefc8, v3
	s_nop 0
	v_cndmask_b32_e32 v44, v202, v44, vcc
	v_cmp_lt_u32_e32 vcc, s68, v4
	v_add_u32_e32 v4, 0xffffefe7, v3
	s_nop 0
	v_cndmask_b32_e32 v28, v202, v28, vcc
	v_cmp_lt_u32_e32 vcc, s68, v4
	v_add_u32_e32 v4, 0xffffefc7, v3
	s_nop 0
	v_cndmask_b32_e32 v45, v202, v45, vcc
	v_cmp_lt_u32_e32 vcc, s68, v4
	v_add_u32_e32 v4, 0xffffefe6, v3
	s_nop 0
	v_cndmask_b32_e32 v29, v202, v29, vcc
	v_cmp_lt_u32_e32 vcc, s68, v4
	v_add_u32_e32 v4, 0xffffefc6, v3
	s_nop 0
	v_cndmask_b32_e32 v46, v202, v46, vcc
	v_cmp_lt_u32_e32 vcc, s68, v4
	v_add_u32_e32 v4, 0xffffefe5, v3
	v_add_u32_e32 v3, 0xffffefc5, v3
	v_cndmask_b32_e32 v30, v202, v30, vcc
	v_cmp_lt_u32_e32 vcc, s68, v4
	s_nop 1
	v_cndmask_b32_e32 v47, v202, v47, vcc
	v_cmp_lt_u32_e32 vcc, s68, v3
	s_nop 1
	v_cndmask_b32_e32 v31, v202, v31, vcc
.LBB0_385:
	v_and_b32_e32 v3, 0xf0, v49
	v_lshlrev_b32_e32 v4, 8, v201
	v_bitop3_b32 v4, v0, v4, v3 bitop3:0xde
	s_nop 5
	v_max_f32_e32 v3, v33, v33
	v_max_f32_e32 v5, v32, v32
	v_max_f32_e32 v3, v5, v3
	v_max3_f32 v3, v3, v34, v35
	v_max3_f32 v3, v3, v36, v37
	v_max3_f32 v3, v3, v38, v39
	v_max3_f32 v3, v3, v40, v41
	v_max3_f32 v3, v3, v42, v43
	v_max3_f32 v3, v3, v44, v45
	v_max3_f32 v3, v3, v46, v47
	v_max3_f32 v3, v3, v16, v17
	v_max3_f32 v3, v3, v18, v19
	v_max3_f32 v3, v3, v20, v21
	v_max3_f32 v3, v3, v22, v23
	v_max3_f32 v3, v3, v24, v25
	v_max3_f32 v3, v3, v26, v27
	v_max3_f32 v3, v3, v28, v29
	v_max3_f32 v3, v3, v30, v31
	v_mov_b32_e32 v5, v3
	s_nop 1
	v_permlane32_swap_b32_e32 v3, v5
	v_max_f32_e32 v5, v5, v5
	v_max_f32_e32 v3, v3, v3
	v_max_f32_e32 v3, v3, v5
	v_add_f32_e32 v5, 0x7149f2ca, v3
	v_mul_f32_e32 v5, 0x3db504f3, v5
	v_cmp_ge_f32_e32 vcc, s69, v5
	s_cmp_eq_u64 vcc, exec
	s_cselect_b64 s[6:7], -1, 0
	s_and_b64 vcc, exec, s[4:5]
	v_add_u32_e32 v205, 0, v4
	s_cbranch_vccnz .LBB0_387
	s_waitcnt vmcnt(0)
	ds_write_b128 v218, v[98:101] offset:16384
	ds_write_b128 v219, v[102:105] offset:16384
	ds_write_b128 v205, v[106:109] offset:49152
	ds_write_b128 v205, v[110:113] offset:57344
.LBB0_387:
	v_max_f32_e32 v3, 0xf149f2ca, v3
	v_cndmask_b32_e64 v182, v3, v192, s[6:7]
	v_sub_f32_e32 v3, 0xf149f2ca, v3
	v_mul_f32_e32 v3, 0x3e0293ee, v3
	v_exp_f32_e32 v3, v3
	v_mul_f32_e32 v4, 0xbe0293ee, v182
	s_and_b32 s4, s33, 0x3fffffc0
	v_and_b32_e32 v206, 63, v49
	v_fmamk_f32 v5, v32, 0x3e0293ee, v4
	s_lshl_b32 s4, s4, 2
	v_fmamk_f32 v6, v33, 0x3e0293ee, v4
	v_fmamk_f32 v7, v34, 0x3e0293ee, v4
	v_fmamk_f32 v8, v35, 0x3e0293ee, v4
	v_fmamk_f32 v9, v36, 0x3e0293ee, v4
	v_fmamk_f32 v10, v37, 0x3e0293ee, v4
	v_fmamk_f32 v11, v38, 0x3e0293ee, v4
	v_fmamk_f32 v12, v39, 0x3e0293ee, v4
	v_fmamk_f32 v13, v40, 0x3e0293ee, v4
	v_fmamk_f32 v14, v41, 0x3e0293ee, v4
	v_fmamk_f32 v15, v42, 0x3e0293ee, v4
	v_fmamk_f32 v32, v43, 0x3e0293ee, v4
	v_fmamk_f32 v33, v44, 0x3e0293ee, v4
	v_fmamk_f32 v34, v45, 0x3e0293ee, v4
	v_fmamk_f32 v35, v46, 0x3e0293ee, v4
	v_fmamk_f32 v36, v47, 0x3e0293ee, v4
	v_pk_fma_f32 v[114:115], v[30:31], s[16:17], v[4:5] op_sel_hi:[1,0,0]
	v_pk_fma_f32 v[116:117], v[28:29], s[16:17], v[4:5] op_sel_hi:[1,0,0]
	v_pk_fma_f32 v[118:119], v[26:27], s[16:17], v[4:5] op_sel_hi:[1,0,0]
	v_pk_fma_f32 v[120:121], v[24:25], s[16:17], v[4:5] op_sel_hi:[1,0,0]
	v_pk_fma_f32 v[122:123], v[22:23], s[16:17], v[4:5] op_sel_hi:[1,0,0]
	v_pk_fma_f32 v[124:125], v[20:21], s[16:17], v[4:5] op_sel_hi:[1,0,0]
	v_pk_fma_f32 v[126:127], v[18:19], s[16:17], v[4:5] op_sel_hi:[1,0,0]
	v_pk_fma_f32 v[128:129], v[16:17], s[16:17], v[4:5] op_sel_hi:[1,0,0]
	s_add_i32 s4, s4, 0
	v_lshlrev_b32_e32 v4, 4, v206
	v_exp_f32_e32 v175, v5
	v_exp_f32_e32 v177, v6
	v_exp_f32_e32 v173, v7
	v_exp_f32_e32 v176, v8
	v_exp_f32_e32 v171, v9
	v_exp_f32_e32 v174, v10
	v_exp_f32_e32 v170, v11
	v_exp_f32_e32 v172, v12
	v_exp_f32_e32 v164, v13
	v_exp_f32_e32 v167, v14
	v_exp_f32_e32 v163, v15
	v_exp_f32_e32 v165, v32
	v_exp_f32_e32 v162, v33
	v_exp_f32_e32 v169, v34
	v_exp_f32_e32 v166, v35
	v_exp_f32_e32 v168, v36
	v_cndmask_b32_e64 v220, v3, 1.0, s[6:7]
	s_add_i32 s6, s4, 0x10000
	v_lshlrev_b32_e32 v3, 3, v206
	v_and_b32_e32 v4, 0xc0, v4
	v_lshlrev_b32_e32 v5, 1, v206
	v_and_or_b32 v4, v3, 24, v4
	v_and_b32_e32 v5, 32, v5
	v_and_b32_e32 v3, 0x100, v3
	s_cmp_lg_u32 0, -1
	v_or3_b32 v3, v4, v5, v3
	s_cselect_b32 s4, 0, 0
	v_add_u32_e32 v209, s4, v3
	v_mov_b32_e32 v17, 0
	s_cmp_lt_i32 s27, 3
	v_cmp_gt_u32_e64 s[4:5], 32, v206
	v_lshl_add_u32 v208, v212, 2, s6
	v_lshl_add_u32 v207, v2, 2, s6
	s_waitcnt lgkmcnt(0)
	s_barrier
	s_cbranch_scc1 .LBB0_407
	s_lshl_b32 s6, s39, 8
	s_addk_i32 s6, 0xfc00
	v_lshl_add_u32 v221, v48, 4, s6
	s_add_i32 s6, s1, 0xc0
	v_add_u32_e32 v3, s6, v212
	v_sub_u32_e32 v2, v3, v2
	v_mov_b32_e32 v213, 0
	v_mov_b32_e32 v203, v252
	s_mov_b32 s33, 2
	v_subrev_u32_e32 v222, s38, v2
	s_addk_i32 s38, 0xff80
	v_mov_b32_e32 v66, 0
	v_mov_b32_e32 v67, v213
	v_mov_b32_e32 v68, v213
	v_mov_b32_e32 v69, v213
	v_mov_b32_e32 v70, v213
	v_mov_b32_e32 v71, v213
	v_mov_b32_e32 v72, v213
	v_mov_b32_e32 v73, v213
	v_mov_b32_e32 v74, v213
	v_mov_b32_e32 v75, v213
	v_mov_b32_e32 v76, v213
	v_mov_b32_e32 v77, v213
	v_mov_b32_e32 v78, v213
	v_mov_b32_e32 v79, v213
	v_mov_b32_e32 v80, v213
	v_mov_b32_e32 v81, v213
	v_mov_b32_e32 v34, 0
	v_mov_b32_e32 v35, v213
	v_mov_b32_e32 v36, v213
	v_mov_b32_e32 v37, v213
	v_mov_b32_e32 v38, v213
	v_mov_b32_e32 v39, v213
	v_mov_b32_e32 v40, v213
	v_mov_b32_e32 v41, v213
	v_mov_b32_e32 v42, v213
	v_mov_b32_e32 v43, v213
	v_mov_b32_e32 v44, v213
	v_mov_b32_e32 v45, v213
	v_mov_b32_e32 v46, v213
	v_mov_b32_e32 v47, v213
	v_mov_b32_e32 v48, v213
	v_mov_b32_e32 v49, v213
	v_mov_b32_e32 v18, 0
	v_mov_b32_e32 v19, v213
	v_mov_b32_e32 v20, v213
	v_mov_b32_e32 v21, v213
	v_mov_b32_e32 v22, v213
	v_mov_b32_e32 v23, v213
	v_mov_b32_e32 v24, v213
	v_mov_b32_e32 v25, v213
	v_mov_b32_e32 v26, v213
	v_mov_b32_e32 v27, v213
	v_mov_b32_e32 v28, v213
	v_mov_b32_e32 v29, v213
	v_mov_b32_e32 v30, v213
	v_mov_b32_e32 v31, v213
	v_mov_b32_e32 v32, v213
	v_mov_b32_e32 v33, v213
	v_mov_b32_e32 v2, 0
	v_mov_b32_e32 v3, v213
	v_mov_b32_e32 v4, v213
	v_mov_b32_e32 v5, v213
	v_mov_b32_e32 v6, v213
	v_mov_b32_e32 v7, v213
	v_mov_b32_e32 v8, v213
	v_mov_b32_e32 v9, v213
	v_mov_b32_e32 v10, v213
	v_mov_b32_e32 v11, v213
	v_mov_b32_e32 v12, v213
	v_mov_b32_e32 v13, v213
	v_mov_b32_e32 v14, v213
	v_mov_b32_e32 v15, v213
	v_mov_b32_e32 v16, v213
	v_mov_b32_e32 v17, v213
	s_lshl_b32 s32, s38, 8
	s_sub_u32 s32, s32, 0x4000
	s_add_u32 s98, s56, s32
	s_addc_u32 s99, s57, 0
	s_add_u32 s100, s54, s32
	s_addc_u32 s101, s55, 0
	v_readfirstlane_b32 s32, v254
	s_lshr_b32 s32, s32, 6
	s_lshl_b32 s32, s32, 11
	v_and_b32_e32 v218, 3, v254
	v_lshlrev_b32_e32 v218, 4, v218
	v_bfe_u32 v223, v254, 5, 1
	v_lshl_or_b32 v218, v223, 6, v218
	v_bfe_u32 v223, v254, 2, 2
	v_lshl_or_b32 v218, v223, 8, v218
	v_bfe_u32 v223, v254, 6, 1
	v_lshl_or_b32 v218, v223, 10, v218
	v_bfe_u32 v223, v254, 4, 1
	v_lshl_or_b32 v218, v223, 11, v218
	v_bfe_u32 v223, v254, 7, 2
	v_lshl_or_b32 v218, v223, 12, v218
	v_lshrrev_b32_e32 v223, 6, v254
	v_bfe_u32 v224, v254, 4, 2
	v_lshl_or_b32 v223, v223, 3, v224
	v_and_b32_e32 v224, 15, v223
	v_and_b32_e32 v227, 15, v254
	v_xor_b32_e32 v227, v227, v224
	v_lshlrev_b32_e32 v227, 4, v227
	v_lshl_or_b32 v219, v223, 8, v227
.LBB0_389:
	ds_read_b128 v[98:101], v214 offset:49152
	ds_read_b128 v[102:105], v196 offset:49152
	ds_read_b128 v[106:109], v214 offset:57344
	ds_read_b128 v[110:113], v196 offset:57344
	ds_read_b128 v[178:181], v215 offset:49152
	ds_read_b128 v[184:187], v197 offset:49152
	ds_read_b128 v[188:191], v215 offset:57344
	ds_read_b128 v[226:229], v197 offset:57344
	s_waitcnt lgkmcnt(7)
	v_mfma_f32_32x32x16_bf16 v[50:65], v[98:101], v[158:161], v[50:65]
	ds_read_b128 v[98:101], v216 offset:49152
	ds_read_b128 v[230:233], v198 offset:49152
	ds_read_b128 v[234:237], v216 offset:57344
	ds_read_b128 v[238:241], v198 offset:57344
	ds_read_b128 v[242:245], v217 offset:49152
	ds_read_b128 v[246:249], v199 offset:49152
	ds_read_b128 v[250:253], v217 offset:57344
	ds_read_b128 v[192:195], v199 offset:57344
	v_exp_f32_e32 v128, v128
	v_exp_f32_e32 v129, v129
	v_exp_f32_e32 v126, v126
	v_exp_f32_e32 v127, v127
	v_exp_f32_e32 v124, v124
	v_exp_f32_e32 v125, v125
	s_waitcnt lgkmcnt(11)
	v_mfma_f32_32x32x16_bf16 v[50:65], v[178:181], v[154:157], v[50:65]
	v_exp_f32_e32 v122, v122
	v_exp_f32_e32 v116, v116
	v_exp_f32_e32 v117, v117
	v_exp_f32_e32 v114, v114
	v_exp_f32_e32 v115, v115
	v_cvt_pk_bf16_f32 v178, v175, v177
	v_cvt_pk_bf16_f32 v179, v173, v176
	s_waitcnt lgkmcnt(7)
	v_mfma_f32_32x32x16_bf16 v[50:65], v[98:101], v[150:153], v[50:65]
	v_exp_f32_e32 v101, v118
	v_exp_f32_e32 v118, v119
	v_add_f32_e32 v119, 0, v175
	v_add_f32_e32 v119, v177, v119
	v_add_f32_e32 v119, v173, v119
	v_add_f32_e32 v119, v176, v119
	v_add_f32_e32 v119, v171, v119
	s_waitcnt lgkmcnt(3)
	v_mfma_f32_32x32x16_bf16 v[50:65], v[242:245], v[146:149], v[50:65]
	v_exp_f32_e32 v98, v123
	v_exp_f32_e32 v99, v120
	v_exp_f32_e32 v100, v121
	v_cvt_pk_bf16_f32 v180, v171, v174
	v_cvt_pk_bf16_f32 v181, v170, v172
	s_nop 0
	v_permlane32_swap_b32_e32 v178, v180
	v_mfma_f32_32x32x16_bf16 v[50:65], v[102:105], v[142:145], v[50:65]
	v_add_f32_e32 v102, v174, v119
	v_add_f32_e32 v102, v170, v102
	v_add_f32_e32 v102, v172, v102
	v_add_f32_e32 v102, v164, v102
	v_add_f32_e32 v102, v167, v102
	v_add_f32_e32 v102, v163, v102
	v_add_f32_e32 v102, v165, v102
	v_mfma_f32_32x32x16_bf16 v[50:65], v[184:187], v[138:141], v[50:65]
	v_add_f32_e32 v102, v162, v102
	v_add_f32_e32 v102, v169, v102
	v_add_f32_e32 v102, v166, v102
	v_add_f32_e32 v102, v168, v102
	v_add_f32_e32 v102, v128, v102
	v_add_f32_e32 v102, v129, v102
	v_add_f32_e32 v102, v126, v102
	v_mfma_f32_32x32x16_bf16 v[50:65], v[230:233], v[134:137], v[50:65]
	v_add_f32_e32 v102, v127, v102
	v_add_f32_e32 v102, v124, v102
	v_add_f32_e32 v102, v125, v102
	v_add_f32_e32 v102, v122, v102
	v_add_f32_e32 v102, v98, v102
	v_add_f32_e32 v102, v99, v102
	v_add_f32_e32 v102, v100, v102
	s_waitcnt lgkmcnt(2)
	v_mfma_f32_32x32x16_bf16 v[50:65], v[246:249], v[130:133], v[50:65]
	v_add_f32_e32 v102, v101, v102
	v_add_f32_e32 v102, v118, v102
	v_add_f32_e32 v102, v116, v102
	v_add_f32_e32 v102, v117, v102
	v_add_f32_e32 v102, v114, v102
	v_add_f32_e32 v223, v115, v102
	v_mov_b32_e32 v224, v223
	s_nop 1
	v_permlane32_swap_b32_e32 v223, v224
	v_cvt_pk_bf16_f32 v184, v164, v167
	v_cvt_pk_bf16_f32 v185, v163, v165
	v_cvt_pk_bf16_f32 v186, v162, v169
	v_cvt_pk_bf16_f32 v187, v166, v168
	v_cvt_pk_bf16_f32 v230, v128, v129
	v_cvt_pk_bf16_f32 v231, v126, v127
	v_cvt_pk_bf16_f32 v232, v124, v125
	v_cvt_pk_bf16_f32 v233, v122, v98
	v_cvt_pk_bf16_f32 v242, v99, v100
	v_cvt_pk_bf16_f32 v243, v101, v118
	v_cvt_pk_bf16_f32 v244, v116, v117
	v_cvt_pk_bf16_f32 v245, v114, v115
	v_permlane32_swap_b32_e32 v179, v181
	v_permlane32_swap_b32_e32 v184, v186
	v_permlane32_swap_b32_e32 v185, v187
	v_permlane32_swap_b32_e32 v230, v232
	v_permlane32_swap_b32_e32 v231, v233
	v_permlane32_swap_b32_e32 v242, v244
	v_permlane32_swap_b32_e32 v243, v245
	v_mfma_f32_32x32x16_bf16 v[82:97], v[106:109], v[158:161], v[82:97]
	s_add_i32 s6, s38, 63
	v_mfma_f32_32x32x16_bf16 v[82:97], v[188:191], v[154:157], v[82:97]
	v_mfma_f32_32x32x16_bf16 v[82:97], v[234:237], v[150:153], v[82:97]
	s_waitcnt lgkmcnt(1)
	v_mfma_f32_32x32x16_bf16 v[82:97], v[250:253], v[146:149], v[82:97]
	v_mfma_f32_32x32x16_bf16 v[82:97], v[110:113], v[142:145], v[82:97]
	v_add_u32_e32 v110, 0x100, v221
	global_load_dwordx4 v[114:117], v110, s[52:53]
	global_load_dwordx4 v[118:121], v110, s[52:53] offset:32
	global_load_dwordx4 v[98:101], v110, s[52:53] offset:128
	global_load_dwordx4 v[102:105], v110, s[52:53] offset:160
	global_load_dwordx4 v[122:125], v110, s[52:53] offset:64
	global_load_dwordx4 v[126:129], v110, s[52:53] offset:96
	global_load_dwordx4 v[106:109], v110, s[52:53] offset:192
	s_nop 0
	global_load_dwordx4 v[110:113], v110, s[52:53] offset:224
	v_mfma_f32_32x32x16_bf16 v[82:97], v[226:229], v[138:141], v[82:97]
	v_mfma_f32_32x32x16_bf16 v[82:97], v[238:241], v[134:137], v[82:97]
	s_waitcnt lgkmcnt(0)
	v_mfma_f32_32x32x16_bf16 v[82:97], v[192:195], v[130:133], v[82:97]
	s_cmp_eq_u32 s33, 2
	s_cbranch_scc1 .Lat_od_nov
	s_add_i32 m0, s32, 0x4000
	v_add_u32_e32 v229, 0x80, v218
	global_load_lds_dwordx4 v218, s[100:101]
	s_add_i32 m0, s32, 0x4400
	s_nop 0
	global_load_lds_dwordx4 v229, s[100:101]
	s_sub_u32 s100, s100, 0x4000
	s_subb_u32 s101, s101, 0

.LBB0_395:
	v_cndmask_b32_e64 v226, v178, v182, s[6:7]
	v_mul_f32_e32 v178, 0xbe0293ee, v226
	v_fmamk_f32 v50, v50, 0x3e0293ee, v178
	v_fmamk_f32 v51, v51, 0x3e0293ee, v178
	v_fmamk_f32 v52, v52, 0x3e0293ee, v178
	v_fmamk_f32 v53, v53, 0x3e0293ee, v178
	v_fmamk_f32 v54, v54, 0x3e0293ee, v178
	v_fmamk_f32 v55, v55, 0x3e0293ee, v178
	v_fmamk_f32 v56, v56, 0x3e0293ee, v178
	v_fmamk_f32 v57, v57, 0x3e0293ee, v178
	v_fmamk_f32 v58, v58, 0x3e0293ee, v178
	v_fmamk_f32 v59, v59, 0x3e0293ee, v178
	v_fmamk_f32 v60, v60, 0x3e0293ee, v178
	v_fmamk_f32 v61, v61, 0x3e0293ee, v178
	v_fmamk_f32 v62, v62, 0x3e0293ee, v178
	v_fmamk_f32 v63, v63, 0x3e0293ee, v178
	v_fmamk_f32 v64, v64, 0x3e0293ee, v178
	v_fmamk_f32 v65, v65, 0x3e0293ee, v178
	v_exp_f32_e32 v50, v50
	v_exp_f32_e32 v51, v51
	v_exp_f32_e32 v52, v52
	v_exp_f32_e32 v53, v53
	v_exp_f32_e32 v54, v54
	v_exp_f32_e32 v55, v55
	v_exp_f32_e32 v56, v56
	v_exp_f32_e32 v57, v57
	v_exp_f32_e32 v58, v58
	v_exp_f32_e32 v59, v59
	v_exp_f32_e32 v60, v60
	v_exp_f32_e32 v61, v61
	v_exp_f32_e32 v62, v62
	v_exp_f32_e32 v63, v63
	v_exp_f32_e32 v64, v64
	v_exp_f32_e32 v65, v65
	v_fmamk_f32 v82, v82, 0x3e0293ee, v178
	v_fmamk_f32 v83, v83, 0x3e0293ee, v178
	v_fmamk_f32 v84, v84, 0x3e0293ee, v178
	v_fmamk_f32 v85, v85, 0x3e0293ee, v178
	v_fmamk_f32 v86, v86, 0x3e0293ee, v178
	v_fmamk_f32 v87, v87, 0x3e0293ee, v178
	v_fmamk_f32 v88, v88, 0x3e0293ee, v178
	v_fmamk_f32 v89, v89, 0x3e0293ee, v178
	v_fmamk_f32 v90, v90, 0x3e0293ee, v178
	v_fmamk_f32 v91, v91, 0x3e0293ee, v178
	v_fmamk_f32 v92, v92, 0x3e0293ee, v178
	v_fmamk_f32 v93, v93, 0x3e0293ee, v178
	v_fmamk_f32 v94, v94, 0x3e0293ee, v178
	v_fmamk_f32 v95, v95, 0x3e0293ee, v178
	v_fmamk_f32 v96, v96, 0x3e0293ee, v178
	v_fmac_f32_e32 v178, 0x3e0293ee, v97
	s_waitcnt lgkmcnt(0)
	s_waitcnt vmcnt(0)
	s_barrier
	ds_read_b128 v[230:233], v214 offset:32768
	ds_read_b128 v[234:237], v214 offset:40960
	ds_read_b128 v[238:241], v215 offset:32768
	ds_read_b128 v[242:245], v215 offset:40960
	ds_read_b128 v[180:183], v216 offset:32768
	ds_read_b128 v[184:187], v216 offset:40960
	ds_read_b128 v[246:249], v217 offset:32768
	ds_read_b128 v[250:253], v217 offset:40960
	v_exp_f32_e32 v97, v178
	v_add_f32_e32 v178, 0, v50
	v_add_f32_e32 v178, v51, v178
	s_waitcnt lgkmcnt(7)
	v_mfma_f32_32x32x16_bf16 v[114:129], v[230:233], v[158:161], v[114:129]
	v_add_f32_e32 v178, v52, v178
	v_add_f32_e32 v178, v53, v178
	v_add_f32_e32 v178, v54, v178
	v_add_f32_e32 v178, v55, v178
	v_add_f32_e32 v178, v56, v178
	v_add_f32_e32 v178, v57, v178
	v_add_f32_e32 v178, v58, v178
	s_waitcnt lgkmcnt(6)
	v_mfma_f32_32x32x16_bf16 v[98:113], v[234:237], v[158:161], v[98:113]
	ds_read_b128 v[230:233], v196 offset:32768
	ds_read_b128 v[234:237], v196 offset:40960
	v_add_f32_e32 v178, v59, v178
	v_add_f32_e32 v178, v60, v178
	v_add_f32_e32 v178, v61, v178
	v_exp_f32_e32 v82, v82
	v_add_f32_e32 v178, v62, v178
	v_exp_f32_e32 v83, v83
	s_waitcnt lgkmcnt(7)
	v_mfma_f32_32x32x16_bf16 v[114:129], v[238:241], v[154:157], v[114:129]
	v_add_f32_e32 v178, v63, v178
	v_exp_f32_e32 v84, v84
	v_add_f32_e32 v178, v64, v178
	v_exp_f32_e32 v85, v85
	v_add_f32_e32 v178, v65, v178
	v_exp_f32_e32 v86, v86
	v_add_f32_e32 v178, v82, v178
	s_waitcnt lgkmcnt(6)
	v_mfma_f32_32x32x16_bf16 v[98:113], v[242:245], v[154:157], v[98:113]
	ds_read_b128 v[238:241], v197 offset:32768
	ds_read_b128 v[242:245], v197 offset:40960
	v_exp_f32_e32 v87, v87
	v_add_f32_e32 v178, v83, v178
	v_exp_f32_e32 v88, v88
	v_add_f32_e32 v178, v84, v178
	v_exp_f32_e32 v89, v89
	v_add_f32_e32 v178, v85, v178
	s_waitcnt lgkmcnt(7)
	v_mfma_f32_32x32x16_bf16 v[114:129], v[180:183], v[150:153], v[114:129]
	v_exp_f32_e32 v90, v90
	v_add_f32_e32 v178, v86, v178
	v_exp_f32_e32 v91, v91
	v_add_f32_e32 v178, v87, v178
	v_exp_f32_e32 v92, v92
	v_add_f32_e32 v178, v88, v178
	v_exp_f32_e32 v93, v93
	s_waitcnt lgkmcnt(6)
	v_mfma_f32_32x32x16_bf16 v[98:113], v[184:187], v[150:153], v[98:113]
	ds_read_b128 v[180:183], v198 offset:32768
	ds_read_b128 v[184:187], v198 offset:40960
	v_add_f32_e32 v178, v89, v178
	v_exp_f32_e32 v94, v94
	v_add_f32_e32 v178, v90, v178
	v_exp_f32_e32 v95, v95
	v_add_f32_e32 v178, v91, v178
	v_exp_f32_e32 v96, v96
	s_waitcnt lgkmcnt(7)
	v_mfma_f32_32x32x16_bf16 v[114:129], v[246:249], v[146:149], v[114:129]
	v_add_f32_e32 v178, v92, v178
	v_add_f32_e32 v178, v93, v178
	v_add_f32_e32 v178, v94, v178
	v_add_f32_e32 v178, v95, v178
	v_add_f32_e32 v178, v96, v178
	v_add_f32_e32 v227, v97, v178
	v_mov_b32_e32 v228, v227
	s_waitcnt lgkmcnt(6)
	v_mfma_f32_32x32x16_bf16 v[98:113], v[250:253], v[146:149], v[98:113]
	ds_read_b128 v[246:249], v199 offset:32768
	ds_read_b128 v[250:253], v199 offset:40960
	v_permlane32_swap_b32_e32 v227, v228
	s_waitcnt lgkmcnt(7)
	v_mfma_f32_32x32x16_bf16 v[114:129], v[230:233], v[142:145], v[114:129]
	s_waitcnt lgkmcnt(6)
	v_mfma_f32_32x32x16_bf16 v[98:113], v[234:237], v[142:145], v[98:113]
	s_waitcnt lgkmcnt(5)
	v_mfma_f32_32x32x16_bf16 v[114:129], v[238:241], v[138:141], v[114:129]
	s_waitcnt lgkmcnt(4)
	v_mfma_f32_32x32x16_bf16 v[98:113], v[242:245], v[138:141], v[98:113]
	s_waitcnt lgkmcnt(3)
	v_mfma_f32_32x32x16_bf16 v[114:129], v[180:183], v[134:137], v[114:129]
	s_waitcnt lgkmcnt(2)
	v_mfma_f32_32x32x16_bf16 v[98:113], v[184:187], v[134:137], v[98:113]
	v_cvt_pk_bf16_f32 v178, v50, v51
	v_cvt_pk_bf16_f32 v179, v52, v53
	s_waitcnt lgkmcnt(1)
	v_mfma_f32_32x32x16_bf16 v[114:129], v[246:249], v[130:133], v[114:129]
	v_cvt_pk_bf16_f32 v180, v54, v55
	v_cvt_pk_bf16_f32 v181, v56, v57
	v_cvt_pk_bf16_f32 v182, v58, v59
	v_cvt_pk_bf16_f32 v183, v60, v61
	s_nop 0
	v_permlane32_swap_b32_e32 v178, v180
	s_waitcnt lgkmcnt(0)
	v_mfma_f32_32x32x16_bf16 v[98:113], v[250:253], v[130:133], v[98:113]
	v_cvt_pk_bf16_f32 v184, v62, v63
	v_cvt_pk_bf16_f32 v185, v64, v65
	v_cvt_pk_bf16_f32 v186, v82, v83
	v_cvt_pk_bf16_f32 v187, v84, v85
	v_cvt_pk_bf16_f32 v188, v86, v87
	v_cvt_pk_bf16_f32 v189, v88, v89
	v_cvt_pk_bf16_f32 v190, v90, v91
	v_cvt_pk_bf16_f32 v191, v92, v93
	v_cvt_pk_bf16_f32 v192, v94, v95
	v_cvt_pk_bf16_f32 v193, v96, v97
	v_permlane32_swap_b32_e32 v179, v181
	v_permlane32_swap_b32_e32 v182, v184
	v_permlane32_swap_b32_e32 v183, v185
	v_permlane32_swap_b32_e32 v186, v188
	v_permlane32_swap_b32_e32 v187, v189
	v_permlane32_swap_b32_e32 v190, v192
	v_permlane32_swap_b32_e32 v191, v193
	s_add_i32 m0, s32, 0x0
	v_add_u32_e32 v229, 0x80, v218
	global_load_lds_dwordx4 v218, s[100:101]
	s_add_i32 m0, s32, 0x400
	s_nop 0
	global_load_lds_dwordx4 v229, s[100:101]
	s_sub_u32 s100, s100, 0x4000
	s_subb_u32 s101, s101, 0
	s_add_i32 s6, s33, 1
	s_cmp_lt_i32 s6, s27
	s_cselect_b64 s[54:55], -1, 0
	s_cmp_ge_i32 s6, s27
	s_cbranch_scc1 .LBB0_397
	global_load_dwordx4 v[50:53], v221, s[52:53]
	global_load_dwordx4 v[54:57], v221, s[52:53] offset:32
	global_load_dwordx4 v[82:85], v221, s[52:53] offset:128
	global_load_dwordx4 v[86:89], v221, s[52:53] offset:160
	global_load_dwordx4 v[58:61], v221, s[52:53] offset:64
	global_load_dwordx4 v[62:65], v221, s[52:53] offset:96
	global_load_dwordx4 v[90:93], v221, s[52:53] offset:192
	global_load_dwordx4 v[94:97], v221, s[52:53] offset:224
	s_add_i32 m0, s32, 0xc000
	v_xor_b32_e32 v229, 64, v219
	global_load_lds_dwordx4 v219, s[98:99]
	s_add_i32 m0, s32, 0xc400
	v_add_u32_e32 v229, 0x400, v229
	global_load_lds_dwordx4 v229, s[98:99]
	s_sub_u32 s98, s98, 0x4000
	s_subb_u32 s99, s99, 0

.LBB0_409:
	s_and_b32 s6, s27, 1
	s_bitcmp1_b32 s27, 0
	s_cselect_b64 s[4:5], -1, 0
	s_cmp_eq_u32 s6, 0
	s_cbranch_scc0 .LBB0_411
	ds_read_b128 v[98:101], v214 offset:49152
	ds_read_b128 v[102:105], v196 offset:49152
	s_waitcnt lgkmcnt(1)
	v_mfma_f32_32x32x16_bf16 v[50:65], v[98:101], v[158:161], v[50:65]
	ds_read_b128 v[98:101], v214 offset:57344
	ds_read_b128 v[106:109], v196 offset:57344
	s_waitcnt lgkmcnt(1)
	v_mfma_f32_32x32x16_bf16 v[82:97], v[98:101], v[158:161], v[82:97]
	ds_read_b128 v[98:101], v215 offset:49152
	ds_read_b128 v[110:113], v197 offset:49152
	s_waitcnt lgkmcnt(1)
	v_mfma_f32_32x32x16_bf16 v[50:65], v[98:101], v[154:157], v[50:65]
	ds_read_b128 v[98:101], v215 offset:57344
	ds_read_b128 v[158:161], v197 offset:57344
	s_waitcnt lgkmcnt(1)
	v_mfma_f32_32x32x16_bf16 v[82:97], v[98:101], v[154:157], v[82:97]
	ds_read_b128 v[98:101], v216 offset:49152
	ds_read_b128 v[154:157], v198 offset:49152
	s_waitcnt lgkmcnt(1)
	v_mfma_f32_32x32x16_bf16 v[50:65], v[98:101], v[150:153], v[50:65]
	ds_read_b128 v[98:101], v216 offset:57344
	ds_read_b128 v[184:187], v198 offset:57344
	s_waitcnt lgkmcnt(1)
	v_mfma_f32_32x32x16_bf16 v[82:97], v[98:101], v[150:153], v[82:97]
	ds_read_b128 v[98:101], v217 offset:49152
	ds_read_b128 v[150:153], v199 offset:49152
	s_waitcnt lgkmcnt(1)
	v_mfma_f32_32x32x16_bf16 v[50:65], v[98:101], v[146:149], v[50:65]
	ds_read_b128 v[98:101], v217 offset:57344
	ds_read_b128 v[188:191], v199 offset:57344
	s_waitcnt lgkmcnt(1)
	v_mfma_f32_32x32x16_bf16 v[82:97], v[98:101], v[146:149], v[82:97]
	v_mfma_f32_32x32x16_bf16 v[50:65], v[102:105], v[142:145], v[50:65]
	v_mfma_f32_32x32x16_bf16 v[82:97], v[106:109], v[142:145], v[82:97]
	v_mfma_f32_32x32x16_bf16 v[50:65], v[110:113], v[138:141], v[50:65]
	v_mfma_f32_32x32x16_bf16 v[82:97], v[158:161], v[138:141], v[82:97]
	v_mfma_f32_32x32x16_bf16 v[50:65], v[154:157], v[134:137], v[50:65]
	v_mfma_f32_32x32x16_bf16 v[82:97], v[184:187], v[134:137], v[82:97]
	v_mfma_f32_32x32x16_bf16 v[50:65], v[150:153], v[130:133], v[50:65]
	s_waitcnt lgkmcnt(0)
	v_mfma_f32_32x32x16_bf16 v[82:97], v[188:191], v[130:133], v[82:97]
